# v23: P2 prompt items run mask-free clones of the two k-step loops (ntok==32: the row-valid selects are no-ops)
# speedup vs baseline: 1.0016x; 1.0016x over previous
.LBB0_524:
	s_cmp_gt_u32 s16, 3
	s_cselect_b64 s[40:41], -1, 0
	s_cmp_lt_u32 s16, 4
	s_cselect_b32 s15, 64, 0x80
	s_lshl_b32 s17, s56, 13
	s_and_b32 s17, s17, 0xffe000
	s_add_u32 s17, s82, s17
	s_addc_u32 s18, s88, 0
	s_and_b64 s[62:63], s[64:65], exec
	s_cselect_b32 s85, s18, s43
	s_cselect_b32 s84, s17, s42
	s_cselect_b32 s15, s15, s14
	s_and_b64 vcc, exec, s[0:1]
	s_cbranch_vccz .LBB0_530
	v_cmp_gt_u32_e64 s[42:43], s13, v61
	s_and_b64 vcc, exec, s[40:41]
	s_nop 0
	v_cndmask_b32_e64 v2, 0, v61, s[42:43]
	v_add_u32_e32 v50, s12, v2
	s_cbranch_vccz .LBB0_531
	s_lshl_b32 s0, s16, 7
	v_mov_b64_e32 v[2:3], s[58:59]
	s_add_i32 s62, s0, 0xfffffe00
	v_mad_i64_i32 v[2:3], s[0:1], v50, s89, v[2:3]
	s_mov_b32 s63, s61
	v_lshl_add_u64 v[2:3], s[62:63], 1, v[2:3]
	v_lshlrev_b32_e32 v56, 1, v60
	v_lshl_add_u64 v[34:35], v[2:3], 0, v[56:57]
	v_add_co_u32_e32 v2, vcc, 0x1000, v34
	s_mov_b64 s[0:1], 0x1000
	s_nop 0
	v_addc_co_u32_e32 v3, vcc, 0, v35, vcc
	global_load_dwordx4 v[22:25], v[2:3], off
	global_load_dwordx4 v[18:21], v[34:35], off offset:3072
	v_mov_b32_e32 v2, 0
	s_mov_b32 s17, 0
	s_mov_b32 s57, 16
	v_lshl_add_u32 v38, s16, 9, v182
	v_mov_b32_e32 v39, v63
	v_mov_b32_e32 v40, v184
	v_mov_b32_e32 v3, v2
	v_mov_b32_e32 v4, v2
	v_mov_b32_e32 v5, v2
	v_mov_b32_e32 v6, v2
	v_mov_b32_e32 v7, v2
	v_mov_b32_e32 v8, v2
	v_mov_b32_e32 v9, v2
	v_mov_b32_e32 v10, v2
	v_mov_b32_e32 v11, v2
	v_mov_b32_e32 v12, v2
	v_mov_b32_e32 v13, v2
	v_mov_b32_e32 v14, v2
	v_mov_b32_e32 v15, v2
	v_mov_b32_e32 v16, v2
	v_lshl_add_u64 v[36:37], v[34:35], 0, s[0:1]
	v_mov_b32_e32 v17, v2
	s_waitcnt vmcnt(1)
	v_lshlrev_b32_e32 v33, 16, v22
	v_and_b32_e32 v32, 0xffff0000, v22
	v_lshlrev_b32_e32 v31, 16, v23
	v_and_b32_e32 v30, 0xffff0000, v23
	v_lshlrev_b32_e32 v29, 16, v24
	v_and_b32_e32 v28, 0xffff0000, v24
	v_lshlrev_b32_e32 v27, 16, v25
	v_and_b32_e32 v26, 0xffff0000, v25
	s_mov_b32 s99, 0
	v_lshl_add_u64 v[240:241], v[34:35], 0, 32
	v_lshl_add_u64 v[242:243], v[36:37], 0, 32
	global_load_dwordx4 v[232:235], v[240:241], off offset:3072
	global_load_dwordx4 v[236:239], v[242:243], off
	s_cmp_eq_u32 s13, 32
	s_cbranch_scc1 .Lh32_528
	s_branch .LBB0_528

.Lp2h_mid:
	ds_read_b128 v[46:49], v41
	ds_read_b128 v[52:55], v41 offset:16
	v_mul_f32_e64 v41, |v33|, s80
	v_exp_f32_e32 v80, v41
	v_mul_f32_e64 v41, |v32|, s80
	v_exp_f32_e32 v81, v41
	v_mul_f32_e64 v41, |v31|, s80
	v_exp_f32_e32 v82, v41
	v_mul_f32_e64 v41, |v30|, s80
	v_exp_f32_e32 v83, v41
	v_mul_f32_e64 v41, |v29|, s80
	v_exp_f32_e32 v84, v41
	v_mul_f32_e64 v41, |v28|, s80
	v_exp_f32_e32 v85, v41
	v_mul_f32_e64 v41, |v27|, s80
	v_exp_f32_e32 v86, v41
	v_mul_f32_e64 v41, |v26|, s80
	v_exp_f32_e32 v87, v41
	v_add_f32_e32 v41, 1.0, v80
	v_rcp_f32_e32 v88, v41
	v_add_f32_e32 v41, 1.0, v81
	v_rcp_f32_e32 v89, v41
	v_add_f32_e32 v41, 1.0, v82
	v_rcp_f32_e32 v90, v41
	v_add_f32_e32 v41, 1.0, v83
	v_rcp_f32_e32 v91, v41
	v_add_f32_e32 v41, 1.0, v84
	v_rcp_f32_e32 v92, v41
	v_add_f32_e32 v41, 1.0, v85
	v_rcp_f32_e32 v93, v41
	v_add_f32_e32 v41, 1.0, v86
	v_pk_mul_f32 v[80:81], v[80:81], v[88:89]
	v_cmp_nle_f32_e32 vcc, 0, v33
	v_rcp_f32_e32 v94, v41
	v_add_f32_e32 v41, 1.0, v87
	v_cndmask_b32_e32 v33, v80, v88, vcc
	s_waitcnt lgkmcnt(1)
	v_pk_add_f32 v[96:97], v[46:47], 1.0 op_sel_hi:[1,0] neg_lo:[1,0] neg_hi:[1,0]
	v_cmp_nle_f32_e64 s[0:1], 0, v32
	v_rcp_f32_e32 v95, v41
	v_mul_f32_e32 v41, v96, v33
	v_cndmask_b32_e64 v33, v89, v81, s[0:1]
	v_cndmask_b32_e32 v32, v88, v80, vcc
	v_cndmask_b32_e64 v51, v81, v89, s[0:1]
	v_pk_fma_f32 v[32:33], v[96:97], v[32:33], v[46:47]
	v_pk_mul_f32 v[46:47], v[82:83], v[90:91]
	v_cmp_nle_f32_e32 vcc, 0, v31
	v_cmp_nle_f32_e64 s[0:1], 0, v30
	v_pk_add_f32 v[80:81], v[48:49], 1.0 op_sel_hi:[1,0] neg_lo:[1,0] neg_hi:[1,0]
	v_cndmask_b32_e32 v31, v46, v90, vcc
	v_cndmask_b32_e32 v30, v90, v46, vcc
	v_cndmask_b32_e64 v46, v47, v91, s[0:1]
	v_mul_f32_e32 v56, v80, v31
	v_cndmask_b32_e64 v31, v91, v47, s[0:1]
	v_mul_f32_e32 v71, v81, v46
	v_pk_mul_f32 v[46:47], v[84:85], v[92:93]
	v_cmp_nle_f32_e32 vcc, 0, v29
	v_cmp_nle_f32_e64 s[0:1], 0, v28
	v_pk_fma_f32 v[30:31], v[80:81], v[30:31], v[48:49]
	v_cndmask_b32_e32 v29, v46, v92, vcc
	s_waitcnt lgkmcnt(0)
	v_pk_add_f32 v[48:49], v[52:53], 1.0 op_sel_hi:[1,0] neg_lo:[1,0] neg_hi:[1,0]
	v_cndmask_b32_e32 v28, v92, v46, vcc
	v_cndmask_b32_e64 v46, v47, v93, s[0:1]
	v_mul_f32_e32 v73, v48, v29
	v_cndmask_b32_e64 v29, v93, v47, s[0:1]
	v_mul_f32_e32 v75, v49, v46
	v_pk_mul_f32 v[46:47], v[86:87], v[94:95]
	v_cmp_nle_f32_e32 vcc, 0, v27
	v_pk_fma_f32 v[28:29], v[48:49], v[28:29], v[52:53]
	v_pk_add_f32 v[48:49], v[54:55], 1.0 op_sel_hi:[1,0] neg_lo:[1,0] neg_hi:[1,0]
	v_cndmask_b32_e32 v27, v46, v94, vcc
	v_cmp_nle_f32_e64 s[0:1], 0, v26
	v_mul_f32_e32 v77, v48, v27
	v_cndmask_b32_e32 v26, v94, v46, vcc
	v_cndmask_b32_e64 v27, v95, v47, s[0:1]
	v_cndmask_b32_e64 v52, v47, v95, s[0:1]
	v_and_b32_e32 v47, 0xffff0000, v42
	v_pk_fma_f32 v[26:27], v[48:49], v[26:27], v[54:55]
	v_mul_f32_e32 v48, 0xbfb8aa3b, v47
	v_exp_f32_e32 v48, v48
	v_mul_f32_e32 v79, v49, v52
	v_lshlrev_b32_e32 v46, 16, v42
	v_and_b32_e32 v49, 0xffff0000, v43
	v_add_f32_e32 v52, 1.0, v48
	v_lshlrev_b32_e32 v48, 16, v43
	v_mul_f32_e32 v43, 0xbfb8aa3b, v48
	v_mul_f32_e32 v42, 0xbfb8aa3b, v46
	v_exp_f32_e32 v53, v43
	v_mul_f32_e32 v43, 0xbfb8aa3b, v49
	v_exp_f32_e32 v42, v42
	v_exp_f32_e32 v54, v43
	v_rcp_f32_e32 v43, v52
	v_add_f32_e32 v52, 1.0, v53
	v_add_f32_e32 v42, 1.0, v42
	v_add_f32_e32 v53, 1.0, v54
	v_rcp_f32_e32 v42, v42
	v_rcp_f32_e32 v52, v52
	v_rcp_f32_e32 v53, v53
	v_cndmask_b32_e64 v32, 1.0, v32, s[42:43]
	v_pk_mul_f32 v[42:43], v[42:43], v[46:47]
	v_cndmask_b32_e64 v33, 1.0, v33, s[42:43]
	v_pk_mul_f32 v[46:47], v[52:53], v[48:49]
	v_cndmask_b32_e64 v30, 1.0, v30, s[42:43]
	v_cndmask_b32_e64 v31, 1.0, v31, s[42:43]
	v_mul_f32_dpp v32, v32, v32 row_shr:1 row_mask:0xf bank_mask:0xf
	v_cndmask_b32_e64 v28, 1.0, v28, s[42:43]
	v_cndmask_b32_e64 v29, 1.0, v29, s[42:43]
	v_mul_f32_dpp v33, v33, v33 row_shr:1 row_mask:0xf bank_mask:0xf
	v_cndmask_b32_e64 v26, 1.0, v26, s[42:43]
	v_cndmask_b32_e64 v27, 1.0, v27, s[42:43]
	v_mul_f32_dpp v30, v30, v30 row_shr:1 row_mask:0xf bank_mask:0xf
	v_and_b32_e32 v55, 0xffff0000, v44
	v_mul_f32_e32 v80, 0xbfb8aa3b, v55
	v_mul_f32_dpp v31, v31, v31 row_shr:1 row_mask:0xf bank_mask:0xf
	v_exp_f32_e32 v80, v80
	v_lshlrev_b32_e32 v54, 16, v44
	v_mul_f32_dpp v28, v28, v28 row_shr:1 row_mask:0xf bank_mask:0xf
	v_add_f32_e32 v82, 1.0, v80
	v_lshlrev_b32_e32 v80, 16, v45
	v_mul_f32_dpp v29, v29, v29 row_shr:1 row_mask:0xf bank_mask:0xf
	v_and_b32_e32 v81, 0xffff0000, v45
	v_mul_f32_e32 v45, 0xbfb8aa3b, v80
	v_mul_f32_dpp v26, v26, v26 row_shr:1 row_mask:0xf bank_mask:0xf
	v_mul_f32_e32 v44, 0xbfb8aa3b, v54
	v_exp_f32_e32 v83, v45
	v_mul_f32_dpp v27, v27, v27 row_shr:1 row_mask:0xf bank_mask:0xf
	v_mul_f32_e32 v45, 0xbfb8aa3b, v81
	v_exp_f32_e32 v44, v44
	v_mul_f32_dpp v32, v32, v32 row_shr:2 row_mask:0xf bank_mask:0xf
	v_exp_f32_e32 v84, v45
	v_add_f32_e32 v44, 1.0, v44
	v_mul_f32_dpp v33, v33, v33 row_shr:2 row_mask:0xf bank_mask:0xf
	v_rcp_f32_e32 v45, v82
	v_add_f32_e32 v82, 1.0, v83
	v_mul_f32_dpp v30, v30, v30 row_shr:2 row_mask:0xf bank_mask:0xf
	v_add_f32_e32 v83, 1.0, v84
	v_rcp_f32_e32 v44, v44
	v_mul_f32_dpp v31, v31, v31 row_shr:2 row_mask:0xf bank_mask:0xf
	v_rcp_f32_e32 v82, v82
	v_rcp_f32_e32 v83, v83
	v_mul_f32_dpp v28, v28, v28 row_shr:2 row_mask:0xf bank_mask:0xf
	v_pk_mul_f32 v[44:45], v[44:45], v[54:55]
	v_pk_mul_f32 v[48:49], v[82:83], v[80:81]
	v_mul_f32_dpp v29, v29, v29 row_shr:2 row_mask:0xf bank_mask:0xf
	v_mul_f32_e32 v51, v97, v51
	v_cndmask_b32_e64 v41, 0, v41, s[42:43]
	v_mul_f32_dpp v26, v26, v26 row_shr:2 row_mask:0xf bank_mask:0xf
	v_cndmask_b32_e64 v51, 0, v51, s[42:43]
	v_cndmask_b32_e64 v56, 0, v56, s[42:43]
	v_mul_f32_dpp v27, v27, v27 row_shr:2 row_mask:0xf bank_mask:0xf
	v_cndmask_b32_e64 v71, 0, v71, s[42:43]
	v_cndmask_b32_e64 v73, 0, v73, s[42:43]
	v_mul_f32_dpp v32, v32, v32 row_shr:4 row_mask:0xf bank_mask:0xf
	v_cndmask_b32_e64 v75, 0, v75, s[42:43]
	v_cndmask_b32_e64 v77, 0, v77, s[42:43]
	v_mul_f32_dpp v33, v33, v33 row_shr:4 row_mask:0xf bank_mask:0xf
	v_cndmask_b32_e64 v79, 0, v79, s[42:43]
	v_cndmask_b32_e64 v49, 0, v49, s[42:43]
	v_mul_f32_dpp v30, v30, v30 row_shr:4 row_mask:0xf bank_mask:0xf
	v_cndmask_b32_e64 v48, 0, v48, s[42:43]
	v_cndmask_b32_e64 v47, 0, v47, s[42:43]
	v_mul_f32_dpp v31, v31, v31 row_shr:4 row_mask:0xf bank_mask:0xf
	v_cndmask_b32_e64 v46, 0, v46, s[42:43]
	v_cndmask_b32_e64 v45, 0, v45, s[42:43]
	v_mul_f32_dpp v28, v28, v28 row_shr:4 row_mask:0xf bank_mask:0xf
	v_cndmask_b32_e64 v44, 0, v44, s[42:43]
	v_cndmask_b32_e64 v43, 0, v43, s[42:43]
	v_mul_f32_dpp v29, v29, v29 row_shr:4 row_mask:0xf bank_mask:0xf
	v_cndmask_b32_e64 v42, 0, v42, s[42:43]
	s_nop 0
	v_mul_f32_dpp v26, v26, v26 row_shr:4 row_mask:0xf bank_mask:0xf
	v_mul_f32_dpp v27, v27, v27 row_shr:4 row_mask:0xf bank_mask:0xf
	v_mul_f32_dpp v32, v32, v32 row_shr:8 row_mask:0xf bank_mask:0xf
	v_mul_f32_dpp v33, v33, v33 row_shr:8 row_mask:0xf bank_mask:0xf
	v_mul_f32_dpp v30, v30, v30 row_shr:8 row_mask:0xf bank_mask:0xf
	v_mul_f32_dpp v31, v31, v31 row_shr:8 row_mask:0xf bank_mask:0xf
	v_mul_f32_dpp v28, v28, v28 row_shr:8 row_mask:0xf bank_mask:0xf
	v_mul_f32_dpp v29, v29, v29 row_shr:8 row_mask:0xf bank_mask:0xf
	v_mul_f32_dpp v26, v26, v26 row_shr:8 row_mask:0xf bank_mask:0xf
	v_mul_f32_dpp v27, v27, v27 row_shr:8 row_mask:0xf bank_mask:0xf
	v_mul_f32_dpp v32, v32, v32 row_bcast:15 row_mask:0xa bank_mask:0xf
	v_mul_f32_dpp v33, v33, v33 row_bcast:15 row_mask:0xa bank_mask:0xf
	v_max_f32_e32 v53, 0x554ad2e, v33
	v_rcp_f32_e32 v85, v53
	v_mul_f32_dpp v30, v30, v30 row_bcast:15 row_mask:0xa bank_mask:0xf
	v_max_f32_e32 v54, 0x554ad2e, v30
	v_rcp_f32_e32 v86, v54
	v_mul_f32_dpp v31, v31, v31 row_bcast:15 row_mask:0xa bank_mask:0xf
	v_max_f32_e32 v55, 0x554ad2e, v31
	v_rcp_f32_e32 v87, v55
	v_mul_f32_dpp v28, v28, v28 row_bcast:15 row_mask:0xa bank_mask:0xf
	v_max_f32_e32 v80, 0x554ad2e, v28
	v_rcp_f32_e32 v88, v80
	v_mul_f32_dpp v29, v29, v29 row_bcast:15 row_mask:0xa bank_mask:0xf
	v_max_f32_e32 v81, 0x554ad2e, v29
	v_rcp_f32_e32 v89, v81
	v_mul_f32_dpp v26, v26, v26 row_bcast:15 row_mask:0xa bank_mask:0xf
	v_max_f32_e32 v82, 0x554ad2e, v26
	v_rcp_f32_e32 v90, v82
	v_mul_f32_dpp v27, v27, v27 row_bcast:15 row_mask:0xa bank_mask:0xf
	v_max_f32_e32 v52, 0x554ad2e, v32
	v_max_f32_e32 v83, 0x554ad2e, v27
	ds_bpermute_b32 v26, v244, v52
	ds_bpermute_b32 v27, v244, v53
	ds_bpermute_b32 v28, v244, v54
	ds_bpermute_b32 v29, v244, v55
	ds_bpermute_b32 v30, v244, v80
	ds_bpermute_b32 v31, v244, v81
	ds_bpermute_b32 v32, v244, v82
	ds_bpermute_b32 v33, v244, v83
	v_rcp_f32_e32 v84, v52
	v_rcp_f32_e32 v91, v83
	v_mul_f32_e32 v41, v41, v84
	v_pk_mul_f32 v[42:43], v[42:43], v[52:53]
	v_mul_f32_e32 v51, v51, v85
	v_mul_f32_e32 v53, v56, v86
	v_pk_mul_f32 v[46:47], v[46:47], v[54:55]
	v_mul_f32_e32 v54, v71, v87
	v_mul_f32_e32 v71, v73, v88
	v_pk_mul_f32 v[44:45], v[44:45], v[80:81]
	v_mul_f32_e32 v75, v75, v89
	v_mul_f32_e32 v77, v77, v90
	v_pk_mul_f32 v[48:49], v[48:49], v[82:83]
	v_mul_f32_e32 v79, v79, v91
	v_cvt_pk_bf16_f32 v42, v42, v43
	v_cvt_pk_bf16_f32 v43, v46, v47
	v_cvt_pk_bf16_f32 v44, v44, v45
	v_cvt_pk_bf16_f32 v45, v48, v49
	v_cvt_pk_bf16_f32 v46, v41, v51
	v_cvt_pk_bf16_f32 v47, v53, v54
	v_cvt_pk_bf16_f32 v48, v71, v75
	v_cvt_pk_bf16_f32 v49, v77, v79
	s_nop 1
	v_mfma_f32_32x32x16_bf16 v[2:17], v[46:49], v[42:45], v[2:17]
	s_waitcnt lgkmcnt(0)
	v_mul_f32_e32 v84, v41, v26
	v_xor_b32_e32 v41, v39, v65
	v_mul_f32_e32 v52, v51, v27
	v_lshl_add_u32 v41, v41, 4, v148
	v_mul_f32_e32 v56, v53, v28
	v_mul_f32_e32 v55, v54, v29
	ds_write_b128 v41, v[42:45] offset:20480
	v_cvt_pk_bf16_f32 v41, v84, v52
	v_mul_f32_e32 v73, v71, v30
	v_mul_f32_e32 v80, v75, v31
	ds_write_b16 v40, v41
	ds_write_b16_d16_hi v40, v41 offset:64
	v_cvt_pk_bf16_f32 v41, v56, v55
	v_mul_f32_e32 v81, v77, v32
	v_mul_f32_e32 v82, v79, v33
	ds_write_b16 v40, v41 offset:128
	ds_write_b16_d16_hi v40, v41 offset:192
	v_cvt_pk_bf16_f32 v41, v73, v80
	ds_write_b16 v40, v41 offset:256
	ds_write_b16_d16_hi v40, v41 offset:320
	v_cvt_pk_bf16_f32 v41, v81, v82
	ds_write_b16 v40, v41 offset:384
	ds_write_b16_d16_hi v40, v41 offset:448
	s_and_saveexec_b64 s[0:1], s[4:5]
	s_cbranch_execz .LBB0_527
	v_add_u32_e32 v41, s17, v183
	ds_write_b128 v41, v[26:29]
	ds_write_b128 v41, v[30:33] offset:16
	s_branch .LBB0_527
.Lh32_527:
	s_or_b64 exec, exec, s[0:1]
	s_add_i32 s17, s17, 64
	s_add_i32 s57, s57, 16
	s_waitcnt vmcnt(2)
	s_xor_b32 s99, s99, 1
	s_cmp_eq_u32 s99, 0
	s_cbranch_scc0 .Lh32_p2h_botB
	v_lshlrev_b32_e32 v33, 16, v22
	v_and_b32_e32 v32, 0xffff0000, v22
	v_lshlrev_b32_e32 v31, 16, v23
	v_and_b32_e32 v30, 0xffff0000, v23
	v_lshlrev_b32_e32 v29, 16, v24
	v_and_b32_e32 v28, 0xffff0000, v24
	v_lshlrev_b32_e32 v27, 16, v25
	v_and_b32_e32 v26, 0xffff0000, v25
	s_branch .Lh32_p2h_botE

.Lh32_p2h_mid:
	ds_read_b128 v[46:49], v41
	ds_read_b128 v[52:55], v41 offset:16
	v_mul_f32_e64 v41, |v33|, s80
	v_exp_f32_e32 v80, v41
	v_mul_f32_e64 v41, |v32|, s80
	v_exp_f32_e32 v81, v41
	v_mul_f32_e64 v41, |v31|, s80
	v_exp_f32_e32 v82, v41
	v_mul_f32_e64 v41, |v30|, s80
	v_exp_f32_e32 v83, v41
	v_mul_f32_e64 v41, |v29|, s80
	v_exp_f32_e32 v84, v41
	v_mul_f32_e64 v41, |v28|, s80
	v_exp_f32_e32 v85, v41
	v_mul_f32_e64 v41, |v27|, s80
	v_exp_f32_e32 v86, v41
	v_mul_f32_e64 v41, |v26|, s80
	v_exp_f32_e32 v87, v41
	v_add_f32_e32 v41, 1.0, v80
	v_rcp_f32_e32 v88, v41
	v_add_f32_e32 v41, 1.0, v81
	v_rcp_f32_e32 v89, v41
	v_add_f32_e32 v41, 1.0, v82
	v_rcp_f32_e32 v90, v41
	v_add_f32_e32 v41, 1.0, v83
	v_rcp_f32_e32 v91, v41
	v_add_f32_e32 v41, 1.0, v84
	v_rcp_f32_e32 v92, v41
	v_add_f32_e32 v41, 1.0, v85
	v_rcp_f32_e32 v93, v41
	v_add_f32_e32 v41, 1.0, v86
	v_pk_mul_f32 v[80:81], v[80:81], v[88:89]
	v_cmp_nle_f32_e32 vcc, 0, v33
	v_rcp_f32_e32 v94, v41
	v_add_f32_e32 v41, 1.0, v87
	v_cndmask_b32_e32 v33, v80, v88, vcc
	s_waitcnt lgkmcnt(1)
	v_pk_add_f32 v[96:97], v[46:47], 1.0 op_sel_hi:[1,0] neg_lo:[1,0] neg_hi:[1,0]
	v_cmp_nle_f32_e64 s[0:1], 0, v32
	v_rcp_f32_e32 v95, v41
	v_mul_f32_e32 v41, v96, v33
	v_cndmask_b32_e64 v33, v89, v81, s[0:1]
	v_cndmask_b32_e32 v32, v88, v80, vcc
	v_cndmask_b32_e64 v51, v81, v89, s[0:1]
	v_pk_fma_f32 v[32:33], v[96:97], v[32:33], v[46:47]
	v_pk_mul_f32 v[46:47], v[82:83], v[90:91]
	v_cmp_nle_f32_e32 vcc, 0, v31
	v_cmp_nle_f32_e64 s[0:1], 0, v30
	v_pk_add_f32 v[80:81], v[48:49], 1.0 op_sel_hi:[1,0] neg_lo:[1,0] neg_hi:[1,0]
	v_cndmask_b32_e32 v31, v46, v90, vcc
	v_cndmask_b32_e32 v30, v90, v46, vcc
	v_cndmask_b32_e64 v46, v47, v91, s[0:1]
	v_mul_f32_e32 v56, v80, v31
	v_cndmask_b32_e64 v31, v91, v47, s[0:1]
	v_mul_f32_e32 v71, v81, v46
	v_pk_mul_f32 v[46:47], v[84:85], v[92:93]
	v_cmp_nle_f32_e32 vcc, 0, v29
	v_cmp_nle_f32_e64 s[0:1], 0, v28
	v_pk_fma_f32 v[30:31], v[80:81], v[30:31], v[48:49]
	v_cndmask_b32_e32 v29, v46, v92, vcc
	s_waitcnt lgkmcnt(0)
	v_pk_add_f32 v[48:49], v[52:53], 1.0 op_sel_hi:[1,0] neg_lo:[1,0] neg_hi:[1,0]
	v_cndmask_b32_e32 v28, v92, v46, vcc
	v_cndmask_b32_e64 v46, v47, v93, s[0:1]
	v_mul_f32_e32 v73, v48, v29
	v_cndmask_b32_e64 v29, v93, v47, s[0:1]
	v_mul_f32_e32 v75, v49, v46
	v_pk_mul_f32 v[46:47], v[86:87], v[94:95]
	v_cmp_nle_f32_e32 vcc, 0, v27
	v_pk_fma_f32 v[28:29], v[48:49], v[28:29], v[52:53]
	v_pk_add_f32 v[48:49], v[54:55], 1.0 op_sel_hi:[1,0] neg_lo:[1,0] neg_hi:[1,0]
	v_cndmask_b32_e32 v27, v46, v94, vcc
	v_cmp_nle_f32_e64 s[0:1], 0, v26
	v_mul_f32_e32 v77, v48, v27
	v_cndmask_b32_e32 v26, v94, v46, vcc
	v_cndmask_b32_e64 v27, v95, v47, s[0:1]
	v_cndmask_b32_e64 v52, v47, v95, s[0:1]
	v_and_b32_e32 v47, 0xffff0000, v42
	v_pk_fma_f32 v[26:27], v[48:49], v[26:27], v[54:55]
	v_mul_f32_e32 v48, 0xbfb8aa3b, v47
	v_exp_f32_e32 v48, v48
	v_mul_f32_e32 v79, v49, v52
	v_lshlrev_b32_e32 v46, 16, v42
	v_and_b32_e32 v49, 0xffff0000, v43
	v_add_f32_e32 v52, 1.0, v48
	v_lshlrev_b32_e32 v48, 16, v43
	v_mul_f32_e32 v43, 0xbfb8aa3b, v48
	v_mul_f32_e32 v42, 0xbfb8aa3b, v46
	v_exp_f32_e32 v53, v43
	v_mul_f32_e32 v43, 0xbfb8aa3b, v49
	v_exp_f32_e32 v42, v42
	v_exp_f32_e32 v54, v43
	v_rcp_f32_e32 v43, v52
	v_add_f32_e32 v52, 1.0, v53
	v_add_f32_e32 v42, 1.0, v42
	v_add_f32_e32 v53, 1.0, v54
	v_rcp_f32_e32 v42, v42
	v_rcp_f32_e32 v52, v52
	v_rcp_f32_e32 v53, v53
	v_pk_mul_f32 v[42:43], v[42:43], v[46:47]
	v_pk_mul_f32 v[46:47], v[52:53], v[48:49]
	v_mul_f32_dpp v32, v32, v32 row_shr:1 row_mask:0xf bank_mask:0xf
	v_mul_f32_dpp v33, v33, v33 row_shr:1 row_mask:0xf bank_mask:0xf
	v_mul_f32_dpp v30, v30, v30 row_shr:1 row_mask:0xf bank_mask:0xf
	v_and_b32_e32 v55, 0xffff0000, v44
	v_mul_f32_e32 v80, 0xbfb8aa3b, v55
	v_mul_f32_dpp v31, v31, v31 row_shr:1 row_mask:0xf bank_mask:0xf
	v_exp_f32_e32 v80, v80
	v_lshlrev_b32_e32 v54, 16, v44
	v_mul_f32_dpp v28, v28, v28 row_shr:1 row_mask:0xf bank_mask:0xf
	v_add_f32_e32 v82, 1.0, v80
	v_lshlrev_b32_e32 v80, 16, v45
	v_mul_f32_dpp v29, v29, v29 row_shr:1 row_mask:0xf bank_mask:0xf
	v_and_b32_e32 v81, 0xffff0000, v45
	v_mul_f32_e32 v45, 0xbfb8aa3b, v80
	v_mul_f32_dpp v26, v26, v26 row_shr:1 row_mask:0xf bank_mask:0xf
	v_mul_f32_e32 v44, 0xbfb8aa3b, v54
	v_exp_f32_e32 v83, v45
	v_mul_f32_dpp v27, v27, v27 row_shr:1 row_mask:0xf bank_mask:0xf
	v_mul_f32_e32 v45, 0xbfb8aa3b, v81
	v_exp_f32_e32 v44, v44
	v_mul_f32_dpp v32, v32, v32 row_shr:2 row_mask:0xf bank_mask:0xf
	v_exp_f32_e32 v84, v45
	v_add_f32_e32 v44, 1.0, v44
	v_mul_f32_dpp v33, v33, v33 row_shr:2 row_mask:0xf bank_mask:0xf
	v_rcp_f32_e32 v45, v82
	v_add_f32_e32 v82, 1.0, v83
	v_mul_f32_dpp v30, v30, v30 row_shr:2 row_mask:0xf bank_mask:0xf
	v_add_f32_e32 v83, 1.0, v84
	v_rcp_f32_e32 v44, v44
	v_mul_f32_dpp v31, v31, v31 row_shr:2 row_mask:0xf bank_mask:0xf
	v_rcp_f32_e32 v82, v82
	v_rcp_f32_e32 v83, v83
	v_mul_f32_dpp v28, v28, v28 row_shr:2 row_mask:0xf bank_mask:0xf
	v_pk_mul_f32 v[44:45], v[44:45], v[54:55]
	v_pk_mul_f32 v[48:49], v[82:83], v[80:81]
	v_mul_f32_dpp v29, v29, v29 row_shr:2 row_mask:0xf bank_mask:0xf
	v_mul_f32_e32 v51, v97, v51
	v_mul_f32_dpp v26, v26, v26 row_shr:2 row_mask:0xf bank_mask:0xf
	v_mul_f32_dpp v27, v27, v27 row_shr:2 row_mask:0xf bank_mask:0xf
	v_mul_f32_dpp v32, v32, v32 row_shr:4 row_mask:0xf bank_mask:0xf
	v_mul_f32_dpp v33, v33, v33 row_shr:4 row_mask:0xf bank_mask:0xf
	v_mul_f32_dpp v30, v30, v30 row_shr:4 row_mask:0xf bank_mask:0xf
	v_mul_f32_dpp v31, v31, v31 row_shr:4 row_mask:0xf bank_mask:0xf
	v_mul_f32_dpp v28, v28, v28 row_shr:4 row_mask:0xf bank_mask:0xf
	v_mul_f32_dpp v29, v29, v29 row_shr:4 row_mask:0xf bank_mask:0xf
	s_nop 0
	v_mul_f32_dpp v26, v26, v26 row_shr:4 row_mask:0xf bank_mask:0xf
	v_mul_f32_dpp v27, v27, v27 row_shr:4 row_mask:0xf bank_mask:0xf
	v_mul_f32_dpp v32, v32, v32 row_shr:8 row_mask:0xf bank_mask:0xf
	v_mul_f32_dpp v33, v33, v33 row_shr:8 row_mask:0xf bank_mask:0xf
	v_mul_f32_dpp v30, v30, v30 row_shr:8 row_mask:0xf bank_mask:0xf
	v_mul_f32_dpp v31, v31, v31 row_shr:8 row_mask:0xf bank_mask:0xf
	v_mul_f32_dpp v28, v28, v28 row_shr:8 row_mask:0xf bank_mask:0xf
	v_mul_f32_dpp v29, v29, v29 row_shr:8 row_mask:0xf bank_mask:0xf
	v_mul_f32_dpp v26, v26, v26 row_shr:8 row_mask:0xf bank_mask:0xf
	v_mul_f32_dpp v27, v27, v27 row_shr:8 row_mask:0xf bank_mask:0xf
	v_mul_f32_dpp v32, v32, v32 row_bcast:15 row_mask:0xa bank_mask:0xf
	v_mul_f32_dpp v33, v33, v33 row_bcast:15 row_mask:0xa bank_mask:0xf
	v_max_f32_e32 v53, 0x554ad2e, v33
	v_rcp_f32_e32 v85, v53
	v_mul_f32_dpp v30, v30, v30 row_bcast:15 row_mask:0xa bank_mask:0xf
	v_max_f32_e32 v54, 0x554ad2e, v30
	v_rcp_f32_e32 v86, v54
	v_mul_f32_dpp v31, v31, v31 row_bcast:15 row_mask:0xa bank_mask:0xf
	v_max_f32_e32 v55, 0x554ad2e, v31
	v_rcp_f32_e32 v87, v55
	v_mul_f32_dpp v28, v28, v28 row_bcast:15 row_mask:0xa bank_mask:0xf
	v_max_f32_e32 v80, 0x554ad2e, v28
	v_rcp_f32_e32 v88, v80
	v_mul_f32_dpp v29, v29, v29 row_bcast:15 row_mask:0xa bank_mask:0xf
	v_max_f32_e32 v81, 0x554ad2e, v29
	v_rcp_f32_e32 v89, v81
	v_mul_f32_dpp v26, v26, v26 row_bcast:15 row_mask:0xa bank_mask:0xf
	v_max_f32_e32 v82, 0x554ad2e, v26
	v_rcp_f32_e32 v90, v82
	v_mul_f32_dpp v27, v27, v27 row_bcast:15 row_mask:0xa bank_mask:0xf
	v_max_f32_e32 v52, 0x554ad2e, v32
	v_max_f32_e32 v83, 0x554ad2e, v27
	ds_bpermute_b32 v26, v244, v52
	ds_bpermute_b32 v27, v244, v53
	ds_bpermute_b32 v28, v244, v54
	ds_bpermute_b32 v29, v244, v55
	ds_bpermute_b32 v30, v244, v80
	ds_bpermute_b32 v31, v244, v81
	ds_bpermute_b32 v32, v244, v82
	ds_bpermute_b32 v33, v244, v83
	v_rcp_f32_e32 v84, v52
	v_rcp_f32_e32 v91, v83
	v_mul_f32_e32 v41, v41, v84
	v_pk_mul_f32 v[42:43], v[42:43], v[52:53]
	v_mul_f32_e32 v51, v51, v85
	v_mul_f32_e32 v53, v56, v86
	v_pk_mul_f32 v[46:47], v[46:47], v[54:55]
	v_mul_f32_e32 v54, v71, v87
	v_mul_f32_e32 v71, v73, v88
	v_pk_mul_f32 v[44:45], v[44:45], v[80:81]
	v_mul_f32_e32 v75, v75, v89
	v_mul_f32_e32 v77, v77, v90
	v_pk_mul_f32 v[48:49], v[48:49], v[82:83]
	v_mul_f32_e32 v79, v79, v91
	v_cvt_pk_bf16_f32 v42, v42, v43
	v_cvt_pk_bf16_f32 v43, v46, v47
	v_cvt_pk_bf16_f32 v44, v44, v45
	v_cvt_pk_bf16_f32 v45, v48, v49
	v_cvt_pk_bf16_f32 v46, v41, v51
	v_cvt_pk_bf16_f32 v47, v53, v54
	v_cvt_pk_bf16_f32 v48, v71, v75
	v_cvt_pk_bf16_f32 v49, v77, v79
	s_nop 1
	v_mfma_f32_32x32x16_bf16 v[2:17], v[46:49], v[42:45], v[2:17]
	s_waitcnt lgkmcnt(0)
	v_mul_f32_e32 v84, v41, v26
	v_xor_b32_e32 v41, v39, v65
	v_mul_f32_e32 v52, v51, v27
	v_lshl_add_u32 v41, v41, 4, v148
	v_mul_f32_e32 v56, v53, v28
	v_mul_f32_e32 v55, v54, v29
	ds_write_b128 v41, v[42:45] offset:20480
	v_cvt_pk_bf16_f32 v41, v84, v52
	v_mul_f32_e32 v73, v71, v30
	v_mul_f32_e32 v80, v75, v31
	ds_write_b16 v40, v41
	ds_write_b16_d16_hi v40, v41 offset:64
	v_cvt_pk_bf16_f32 v41, v56, v55
	v_mul_f32_e32 v81, v77, v32
	v_mul_f32_e32 v82, v79, v33
	ds_write_b16 v40, v41 offset:128
	ds_write_b16_d16_hi v40, v41 offset:192
	v_cvt_pk_bf16_f32 v41, v73, v80
	ds_write_b16 v40, v41 offset:256
	ds_write_b16_d16_hi v40, v41 offset:320
	v_cvt_pk_bf16_f32 v41, v81, v82
	ds_write_b16 v40, v41 offset:384
	ds_write_b16_d16_hi v40, v41 offset:448
	s_and_saveexec_b64 s[0:1], s[4:5]
	s_cbranch_execz .Lh32_527
	v_add_u32_e32 v41, s17, v183
	ds_write_b128 v41, v[26:29]
	ds_write_b128 v41, v[30:33] offset:16
	s_branch .Lh32_527

.LBB0_561:
	v_ashrrev_i32_e32 v51, 31, v50
	v_readlane_b32 s0, v255, 19
	v_lshlrev_b64 v[2:3], 6, v[50:51]
	v_readlane_b32 s1, v255, 20
	s_lshl_b32 s62, s16, 7
	s_mov_b32 s63, s61
	v_lshl_add_u64 v[2:3], s[0:1], 0, v[2:3]
	global_load_dwordx4 v[16:19], v[2:3], off offset:48
	global_load_dwordx4 v[20:23], v[2:3], off offset:32
	global_load_dwordx4 v[24:27], v[2:3], off offset:16
	global_load_dwordx4 v[28:31], v[2:3], off
	v_mov_b64_e32 v[2:3], s[58:59]
	v_mad_i64_i32 v[2:3], s[0:1], v50, s89, v[2:3]
	v_lshl_add_u64 v[2:3], v[2:3], 0, s[62:63]
	v_lshlrev_b32_e32 v56, 1, v60
	v_lshl_add_u64 v[48:49], v[2:3], 0, v[56:57]
	global_load_dwordx4 v[32:35], v[48:49], off
	global_load_dwordx4 v[36:39], v[48:49], off offset:512
	v_mov_b32_e32 v2, 0
	s_lshl_b32 s17, s16, 6
	v_lshl_add_u32 v56, s16, 8, v59
	s_mov_b32 s57, 0
	s_mov_b32 s63, 16
	v_mov_b32_e32 v71, v63
	v_mov_b32_e32 v73, v184
	v_mov_b32_e32 v3, v2
	v_mov_b32_e32 v4, v2
	v_mov_b32_e32 v5, v2
	v_mov_b32_e32 v6, v2
	v_mov_b32_e32 v7, v2
	v_mov_b32_e32 v8, v2
	v_mov_b32_e32 v9, v2
	v_mov_b32_e32 v10, v2
	v_mov_b32_e32 v11, v2
	v_mov_b32_e32 v12, v2
	v_mov_b32_e32 v13, v2
	v_mov_b32_e32 v14, v2
	v_mov_b32_e32 v15, v2
	s_waitcnt vmcnt(5)
	v_mov_b32_e32 v110, v16
	s_waitcnt vmcnt(4)
	v_mov_b32_e32 v98, v20
	s_waitcnt vmcnt(3)
	v_mov_b32_e32 v86, v24
	s_waitcnt vmcnt(2)
	v_mov_b32_e32 v50, v28
	v_mov_b32_e32 v51, v28
	v_mov_b32_e32 v52, v28
	v_mov_b32_e32 v53, v28
	v_mov_b32_e32 v54, v29
	v_mov_b32_e32 v55, v29
	v_mov_b32_e32 v28, v29
	v_mov_b32_e32 v80, v30
	v_mov_b32_e32 v81, v30
	v_mov_b32_e32 v82, v30
	v_mov_b32_e32 v83, v30
	v_mov_b32_e32 v84, v31
	v_mov_b32_e32 v85, v31
	v_mov_b32_e32 v30, v31
	v_mov_b32_e32 v87, v24
	v_mov_b32_e32 v88, v24
	v_mov_b32_e32 v89, v24
	v_mov_b32_e32 v90, v25
	v_mov_b32_e32 v91, v25
	v_mov_b32_e32 v24, v25
	v_mov_b32_e32 v92, v26
	v_mov_b32_e32 v93, v26
	v_mov_b32_e32 v94, v26
	v_mov_b32_e32 v95, v26
	v_mov_b32_e32 v96, v27
	v_mov_b32_e32 v97, v27
	v_mov_b32_e32 v26, v27
	v_mov_b32_e32 v99, v20
	v_mov_b32_e32 v100, v20
	v_mov_b32_e32 v101, v20
	v_mov_b32_e32 v102, v21
	v_mov_b32_e32 v103, v21
	v_mov_b32_e32 v20, v21
	v_mov_b32_e32 v104, v22
	v_mov_b32_e32 v105, v22
	v_mov_b32_e32 v106, v22
	v_mov_b32_e32 v107, v22
	v_mov_b32_e32 v108, v23
	v_mov_b32_e32 v109, v23
	v_mov_b32_e32 v22, v23
	v_mov_b32_e32 v111, v16
	v_mov_b32_e32 v112, v16
	v_mov_b32_e32 v113, v16
	v_mov_b32_e32 v114, v17
	v_mov_b32_e32 v115, v17
	v_mov_b32_e32 v116, v17
	v_mov_b32_e32 v117, v17
	v_mov_b32_e32 v118, v18
	v_mov_b32_e32 v119, v18
	v_mov_b32_e32 v120, v18
	v_mov_b32_e32 v121, v18
	v_mov_b32_e32 v122, v19
	v_mov_b32_e32 v123, v19
	v_mov_b32_e32 v18, v19
	v_mov_b32_e32 v16, v2
	v_mov_b32_e32 v17, v2
	s_mov_b32 s99, 0
	v_lshl_add_u64 v[240:241], v[48:49], 0, 32
	global_load_dwordx4 v[232:235], v[240:241], off
	global_load_dwordx4 v[236:239], v[240:241], off offset:512
	s_cmp_eq_u32 s13, 32
	s_cbranch_scc1 .Lg32_563
	s_branch .LBB0_563

.Lp2g_mid:
	s_xor_b32 s99, s99, 1
	ds_read_b128 v[124:127], v75 offset:16384
	ds_read_b128 v[128:131], v75 offset:16400
	ds_read_b128 v[188:191], v75
	ds_read_b128 v[192:195], v75 offset:16
	ds_read_b128 v[196:199], v75 offset:1024
	ds_read_b128 v[200:203], v75 offset:1040
	ds_read_b128 v[204:207], v75 offset:2048
	ds_read_b128 v[210:213], v75 offset:2064
	ds_read_b128 v[214:217], v75 offset:3072
	ds_read_b128 v[218:221], v75 offset:3088
	s_waitcnt lgkmcnt(7)
	v_pk_fma_f32 v[126:127], v[52:53], v[190:191], v[126:127]
	v_pk_fma_f32 v[124:125], v[50:51], v[188:189], v[124:125]
	s_waitcnt lgkmcnt(6)
	v_pk_fma_f32 v[130:131], v[52:53], v[194:195], v[130:131]
	v_pk_fma_f32 v[128:129], v[50:51], v[192:193], v[128:129]
	s_waitcnt lgkmcnt(5)
	v_pk_fma_f32 v[126:127], v[28:29], v[198:199], v[126:127]
	v_pk_fma_f32 v[124:125], v[54:55], v[196:197], v[124:125]
	s_waitcnt lgkmcnt(4)
	v_pk_fma_f32 v[130:131], v[28:29], v[202:203], v[130:131]
	v_pk_fma_f32 v[128:129], v[54:55], v[200:201], v[128:129]
	s_waitcnt lgkmcnt(3)
	v_pk_fma_f32 v[126:127], v[82:83], v[206:207], v[126:127]
	v_pk_fma_f32 v[124:125], v[80:81], v[204:205], v[124:125]
	s_waitcnt lgkmcnt(2)
	v_pk_fma_f32 v[130:131], v[82:83], v[212:213], v[130:131]
	v_pk_fma_f32 v[128:129], v[80:81], v[210:211], v[128:129]
	s_waitcnt lgkmcnt(1)
	v_pk_fma_f32 v[132:133], v[30:31], v[216:217], v[126:127]
	v_pk_fma_f32 v[214:215], v[84:85], v[214:215], v[124:125]
	s_waitcnt lgkmcnt(0)
	v_pk_fma_f32 v[216:217], v[30:31], v[220:221], v[130:131]
	v_pk_fma_f32 v[218:219], v[84:85], v[218:219], v[128:129]
	ds_read_b128 v[124:127], v75 offset:4096
	ds_read_b128 v[128:131], v75 offset:4112
	ds_read_b128 v[188:191], v75 offset:5120
	ds_read_b128 v[192:195], v75 offset:5136
	ds_read_b128 v[196:199], v75 offset:6144
	ds_read_b128 v[200:203], v75 offset:6160
	ds_read_b128 v[204:207], v75 offset:7168
	ds_read_b128 v[210:213], v75 offset:7184
	s_waitcnt lgkmcnt(7)
	v_pk_fma_f32 v[126:127], v[88:89], v[126:127], v[132:133]
	v_pk_fma_f32 v[124:125], v[86:87], v[124:125], v[214:215]
	s_waitcnt lgkmcnt(6)
	v_pk_fma_f32 v[130:131], v[88:89], v[130:131], v[216:217]
	v_pk_fma_f32 v[128:129], v[86:87], v[128:129], v[218:219]
	s_waitcnt lgkmcnt(5)
	v_pk_fma_f32 v[126:127], v[24:25], v[190:191], v[126:127]
	v_pk_fma_f32 v[124:125], v[90:91], v[188:189], v[124:125]
	s_waitcnt lgkmcnt(4)
	v_pk_fma_f32 v[130:131], v[24:25], v[194:195], v[130:131]
	v_pk_fma_f32 v[128:129], v[90:91], v[192:193], v[128:129]
	s_waitcnt lgkmcnt(3)
	v_pk_fma_f32 v[126:127], v[94:95], v[198:199], v[126:127]
	v_pk_fma_f32 v[124:125], v[92:93], v[196:197], v[124:125]
	s_waitcnt lgkmcnt(2)
	v_pk_fma_f32 v[130:131], v[94:95], v[202:203], v[130:131]
	v_pk_fma_f32 v[128:129], v[92:93], v[200:201], v[128:129]
	s_waitcnt lgkmcnt(1)
	v_pk_fma_f32 v[132:133], v[26:27], v[206:207], v[126:127]
	v_pk_fma_f32 v[214:215], v[96:97], v[204:205], v[124:125]
	s_waitcnt lgkmcnt(0)
	v_pk_fma_f32 v[216:217], v[26:27], v[212:213], v[130:131]
	v_pk_fma_f32 v[218:219], v[96:97], v[210:211], v[128:129]
	ds_read_b128 v[124:127], v75 offset:8192
	ds_read_b128 v[128:131], v75 offset:8208
	ds_read_b128 v[188:191], v75 offset:9216
	ds_read_b128 v[192:195], v75 offset:9232
	ds_read_b128 v[196:199], v75 offset:10240
	ds_read_b128 v[200:203], v75 offset:10256
	ds_read_b128 v[204:207], v75 offset:11264
	ds_read_b128 v[210:213], v75 offset:11280
	s_waitcnt lgkmcnt(7)
	v_pk_fma_f32 v[126:127], v[100:101], v[126:127], v[132:133]
	v_pk_fma_f32 v[124:125], v[98:99], v[124:125], v[214:215]
	s_waitcnt lgkmcnt(6)
	v_pk_fma_f32 v[130:131], v[100:101], v[130:131], v[216:217]
	v_pk_fma_f32 v[128:129], v[98:99], v[128:129], v[218:219]
	s_waitcnt lgkmcnt(5)
	v_pk_fma_f32 v[126:127], v[20:21], v[190:191], v[126:127]
	v_pk_fma_f32 v[124:125], v[102:103], v[188:189], v[124:125]
	s_waitcnt lgkmcnt(4)
	v_pk_fma_f32 v[130:131], v[20:21], v[194:195], v[130:131]
	v_pk_fma_f32 v[128:129], v[102:103], v[192:193], v[128:129]
	s_waitcnt lgkmcnt(3)
	v_pk_fma_f32 v[126:127], v[106:107], v[198:199], v[126:127]
	v_pk_fma_f32 v[124:125], v[104:105], v[196:197], v[124:125]
	s_waitcnt lgkmcnt(2)
	v_pk_fma_f32 v[130:131], v[106:107], v[202:203], v[130:131]
	v_pk_fma_f32 v[128:129], v[104:105], v[200:201], v[128:129]
	s_waitcnt lgkmcnt(1)
	v_pk_fma_f32 v[132:133], v[22:23], v[206:207], v[126:127]
	v_pk_fma_f32 v[214:215], v[108:109], v[204:205], v[124:125]
	s_waitcnt lgkmcnt(0)
	v_pk_fma_f32 v[216:217], v[22:23], v[212:213], v[130:131]
	v_pk_fma_f32 v[218:219], v[108:109], v[210:211], v[128:129]
	ds_read_b128 v[124:127], v75 offset:12288
	ds_read_b128 v[128:131], v75 offset:12304
	ds_read_b128 v[188:191], v75 offset:13312
	ds_read_b128 v[192:195], v75 offset:13328
	ds_read_b128 v[196:199], v75 offset:14336
	ds_read_b128 v[200:203], v75 offset:14352
	ds_read_b128 v[204:207], v75 offset:15360
	ds_read_b128 v[210:213], v75 offset:15376
	s_waitcnt lgkmcnt(7)
	v_pk_fma_f32 v[124:125], v[110:111], v[124:125], v[214:215]
	s_waitcnt lgkmcnt(6)
	v_pk_fma_f32 v[130:131], v[112:113], v[130:131], v[216:217]
	s_waitcnt lgkmcnt(5)
	v_pk_fma_f32 v[124:125], v[114:115], v[188:189], v[124:125]
	v_pk_fma_f32 v[126:127], v[112:113], v[126:127], v[132:133]
	s_waitcnt lgkmcnt(4)
	v_pk_fma_f32 v[130:131], v[116:117], v[194:195], v[130:131]
	s_waitcnt lgkmcnt(3)
	v_pk_fma_f32 v[124:125], v[118:119], v[196:197], v[124:125]
	v_pk_fma_f32 v[128:129], v[110:111], v[128:129], v[218:219]
	v_pk_fma_f32 v[126:127], v[116:117], v[190:191], v[126:127]
	s_waitcnt lgkmcnt(2)
	v_pk_fma_f32 v[132:133], v[120:121], v[202:203], v[130:131]
	s_waitcnt lgkmcnt(1)
	v_pk_fma_f32 v[130:131], v[122:123], v[204:205], v[124:125]
	v_pk_fma_f32 v[128:129], v[114:115], v[192:193], v[128:129]
	v_pk_fma_f32 v[126:127], v[120:121], v[198:199], v[126:127]
	v_mul_f32_e64 v75, |v130|, s80
	v_pk_fma_f32 v[188:189], v[118:119], v[200:201], v[128:129]
	v_pk_fma_f32 v[128:129], v[18:19], v[206:207], v[126:127]
	v_exp_f32_e32 v75, v75
	s_waitcnt lgkmcnt(0)
	v_pk_fma_f32 v[124:125], v[18:19], v[212:213], v[132:133]
	v_pk_fma_f32 v[126:127], v[122:123], v[210:211], v[188:189]
	v_mul_f32_e64 v132, |v129|, s80
	v_exp_f32_e32 v187, v132
	v_mul_f32_e64 v132, |v126|, s80
	v_exp_f32_e32 v190, v132
	v_mul_f32_e64 v132, |v127|, s80
	v_exp_f32_e32 v191, v132
	v_mul_f32_e64 v132, |v124|, s80
	v_add_f32_e32 v75, 1.0, v75
	v_exp_f32_e32 v192, v132
	v_mul_f32_e64 v132, |v125|, s80
	v_exp_f32_e32 v193, v132
	v_mul_f32_e64 v77, |v131|, s80
	v_log_f32_e32 v75, v75
	v_exp_f32_e32 v77, v77
	v_mul_f32_e64 v79, |v128|, s80
	v_exp_f32_e32 v79, v79
	v_mul_f32_e32 v132, 0x3f317217, v75
	v_fma_f32 v132, v75, s10, -v132
	v_fmac_f32_e32 v132, 0x3377d1cf, v75
	v_fmac_f32_e32 v132, 0x3f317217, v75
	v_min_f32_e32 v130, 0, v130
	v_min_f32_e32 v131, 0, v131
	v_mov_b32_e32 v132, v132
	v_add_f32_e32 v75, 1.0, v77
	v_min_f32_e32 v128, 0, v128
	v_min_f32_e32 v129, 0, v129
	v_log_f32_e32 v75, v75
	v_lshlrev_b32_e32 v194, 16, v46
	v_and_b32_e32 v195, 0xffff0000, v46
	v_lshlrev_b32_e32 v196, 16, v47
	v_mul_f32_e32 v77, 0x3f317217, v75
	v_fma_f32 v77, v75, s10, -v77
	v_fmac_f32_e32 v77, 0x3377d1cf, v75
	v_fmac_f32_e32 v77, 0x3f317217, v75
	v_and_b32_e32 v197, 0xffff0000, v47
	v_lshlrev_b32_e32 v46, 16, v42
	v_mov_b32_e32 v133, v77
	v_add_f32_e32 v75, 1.0, v79
	v_lshlrev_b32_e32 v79, 16, v45
	v_and_b32_e32 v42, 0xffff0000, v42
	v_log_f32_e32 v75, v75
	v_lshlrev_b32_e32 v47, 16, v43
	v_and_b32_e32 v43, 0xffff0000, v43
	v_mul_f32_e32 v203, 0x3e000000, v42
	v_mul_f32_e32 v77, 0x3f317217, v75
	v_fma_f32 v77, v75, s10, -v77
	v_fmac_f32_e32 v77, 0x3377d1cf, v75
	v_fmac_f32_e32 v77, 0x3f317217, v75
	v_mul_f32_e32 v205, 0x3e000000, v43
	v_min_f32_e32 v126, 0, v126
	v_mov_b32_e32 v188, v77
	v_add_f32_e32 v75, 1.0, v187
	v_and_b32_e32 v187, 0xffff0000, v45
	v_lshlrev_b32_e32 v45, 16, v41
	v_log_f32_e32 v75, v75
	v_and_b32_e32 v41, 0xffff0000, v41
	v_mul_f32_e32 v201, 0x3e000000, v41
	v_min_f32_e32 v127, 0, v127
	v_mul_f32_e32 v77, 0x3f317217, v75
	v_fma_f32 v77, v75, s10, -v77
	v_fmac_f32_e32 v77, 0x3377d1cf, v75
	v_fmac_f32_e32 v77, 0x3f317217, v75
	v_mul_f32_e32 v200, 0x3e000000, v45
	v_min_f32_e32 v124, 0, v124
	v_mov_b32_e32 v189, v77
	v_add_f32_e32 v75, 1.0, v190
	v_pk_add_f32 v[42:43], v[128:129], v[188:189] neg_lo:[0,1] neg_hi:[0,1]
	v_min_f32_e32 v125, 0, v125
	v_log_f32_e32 v75, v75
	v_pk_mul_f32 v[42:43], v[42:43], s[92:93] op_sel_hi:[1,0]
	v_mul_f32_e32 v202, 0x3e000000, v46
	v_cndmask_b32_e64 v42, 0, v42, s[42:43]
	v_mul_f32_e32 v77, 0x3f317217, v75
	v_fma_f32 v77, v75, s10, -v77
	v_fmac_f32_e32 v77, 0x3377d1cf, v75
	v_fmac_f32_e32 v77, 0x3f317217, v75
	v_add_f32_dpp v42, v42, v42 row_shr:1 row_mask:0xf bank_mask:0xf bound_ctrl:1
	v_cndmask_b32_e64 v43, 0, v43, s[42:43]
	v_mov_b32_e32 v190, v77
	v_add_f32_e32 v75, 1.0, v191
	v_add_f32_dpp v42, v42, v42 row_shr:2 row_mask:0xf bank_mask:0xf bound_ctrl:1
	v_add_f32_dpp v43, v43, v43 row_shr:1 row_mask:0xf bank_mask:0xf bound_ctrl:1
	v_log_f32_e32 v75, v75
	v_add_f32_dpp v42, v42, v42 row_shr:4 row_mask:0xf bank_mask:0xf bound_ctrl:1
	v_add_f32_dpp v43, v43, v43 row_shr:2 row_mask:0xf bank_mask:0xf bound_ctrl:1
	v_mul_f32_e32 v204, 0x3e000000, v47
	v_mul_f32_e32 v77, 0x3f317217, v75
	v_fma_f32 v77, v75, s10, -v77
	v_fmac_f32_e32 v77, 0x3377d1cf, v75
	v_fmac_f32_e32 v77, 0x3f317217, v75
	v_add_f32_dpp v42, v42, v42 row_shr:8 row_mask:0xf bank_mask:0xf bound_ctrl:1
	v_add_f32_dpp v43, v43, v43 row_shr:4 row_mask:0xf bank_mask:0xf bound_ctrl:1
	v_mov_b32_e32 v191, v77
	v_add_f32_e32 v75, 1.0, v192
	v_add_f32_dpp v43, v43, v43 row_shr:8 row_mask:0xf bank_mask:0xf bound_ctrl:1
	v_cndmask_b32_e64 v128, 0, v187, s[42:43]
	v_log_f32_e32 v75, v75
	v_cndmask_b32_e64 v187, 0, v196, s[42:43]
	v_cndmask_b32_e64 v189, 0, v197, s[42:43]
	v_cndmask_b32_e64 v129, 0, v202, s[42:43]
	v_mul_f32_e32 v77, 0x3f317217, v75
	v_fma_f32 v77, v75, s10, -v77
	v_fmac_f32_e32 v77, 0x3377d1cf, v75
	v_fmac_f32_e32 v77, 0x3f317217, v75
	v_cndmask_b32_e64 v188, 0, v205, s[42:43]
	v_cndmask_b32_e64 v79, 0, v79, s[42:43]
	v_mov_b32_e32 v192, v77
	v_add_f32_e32 v75, 1.0, v193
	s_nop 1
	v_log_f32_e32 v75, v75
	s_nop 0
	v_mul_f32_e32 v77, 0x3f317217, v75
	v_fma_f32 v77, v75, s10, -v77
	v_fmac_f32_e32 v77, 0x3377d1cf, v75
	v_fmac_f32_e32 v77, 0x3f317217, v75
	s_nop 1
	v_mov_b32_e32 v193, v77
	v_lshlrev_b32_e32 v75, 16, v44
	v_and_b32_e32 v77, 0xffff0000, v44
	v_lshlrev_b32_e32 v44, 16, v40
	v_and_b32_e32 v40, 0xffff0000, v40
	v_mul_f32_e32 v199, 0x3e000000, v40
	v_pk_add_f32 v[40:41], v[130:131], v[132:133] neg_lo:[0,1] neg_hi:[0,1]
	v_mul_f32_e32 v198, 0x3e000000, v44
	v_pk_mul_f32 v[40:41], v[40:41], s[92:93] op_sel_hi:[1,0]
	v_pk_add_f32 v[44:45], v[126:127], v[190:191] neg_lo:[0,1] neg_hi:[0,1]
	v_cndmask_b32_e64 v40, 0, v40, s[42:43]
	v_cndmask_b32_e64 v41, 0, v41, s[42:43]
	s_nop 0
	v_add_f32_dpp v40, v40, v40 row_shr:1 row_mask:0xf bank_mask:0xf bound_ctrl:1
	v_add_f32_dpp v41, v41, v41 row_shr:1 row_mask:0xf bank_mask:0xf bound_ctrl:1
	v_pk_mul_f32 v[44:45], v[44:45], s[92:93] op_sel_hi:[1,0]
	v_add_f32_dpp v40, v40, v40 row_shr:2 row_mask:0xf bank_mask:0xf bound_ctrl:1
	v_add_f32_dpp v41, v41, v41 row_shr:2 row_mask:0xf bank_mask:0xf bound_ctrl:1
	v_cndmask_b32_e64 v44, 0, v44, s[42:43]
	v_add_f32_dpp v40, v40, v40 row_shr:4 row_mask:0xf bank_mask:0xf bound_ctrl:1
	v_add_f32_dpp v41, v41, v41 row_shr:4 row_mask:0xf bank_mask:0xf bound_ctrl:1
	v_add_f32_dpp v44, v44, v44 row_shr:1 row_mask:0xf bank_mask:0xf bound_ctrl:1
	v_add_f32_dpp v40, v40, v40 row_shr:8 row_mask:0xf bank_mask:0xf bound_ctrl:1
	v_add_f32_dpp v41, v41, v41 row_shr:8 row_mask:0xf bank_mask:0xf bound_ctrl:1
	v_pk_add_f32 v[46:47], v[124:125], v[192:193] neg_lo:[0,1] neg_hi:[0,1]
	v_add_f32_dpp v40, v40, v40 row_bcast:15 row_mask:0xa bank_mask:0xf
	v_cndmask_b32_e64 v45, 0, v45, s[42:43]
	v_add_f32_dpp v44, v44, v44 row_shr:2 row_mask:0xf bank_mask:0xf bound_ctrl:1
	v_add_f32_dpp v41, v41, v41 row_bcast:15 row_mask:0xa bank_mask:0xf
	v_pk_mul_f32 v[46:47], v[46:47], s[92:93] op_sel_hi:[1,0]
	v_add_f32_dpp v45, v45, v45 row_shr:1 row_mask:0xf bank_mask:0xf bound_ctrl:1
	v_add_f32_dpp v42, v42, v42 row_bcast:15 row_mask:0xa bank_mask:0xf
	v_add_f32_dpp v44, v44, v44 row_shr:4 row_mask:0xf bank_mask:0xf bound_ctrl:1
	v_cndmask_b32_e64 v46, 0, v46, s[42:43]
	v_add_f32_dpp v45, v45, v45 row_shr:2 row_mask:0xf bank_mask:0xf bound_ctrl:1
	v_add_f32_dpp v44, v44, v44 row_shr:8 row_mask:0xf bank_mask:0xf bound_ctrl:1
	v_add_f32_dpp v43, v43, v43 row_bcast:15 row_mask:0xa bank_mask:0xf
	v_add_f32_dpp v46, v46, v46 row_shr:1 row_mask:0xf bank_mask:0xf bound_ctrl:1
	v_add_f32_dpp v45, v45, v45 row_shr:4 row_mask:0xf bank_mask:0xf bound_ctrl:1
	v_cndmask_b32_e64 v47, 0, v47, s[42:43]
	v_add_f32_dpp v46, v46, v46 row_shr:2 row_mask:0xf bank_mask:0xf bound_ctrl:1
	v_add_f32_dpp v45, v45, v45 row_shr:8 row_mask:0xf bank_mask:0xf bound_ctrl:1
	v_add_f32_dpp v44, v44, v44 row_bcast:15 row_mask:0xa bank_mask:0xf
	v_add_f32_dpp v47, v47, v47 row_shr:1 row_mask:0xf bank_mask:0xf bound_ctrl:1
	v_add_f32_dpp v46, v46, v46 row_shr:4 row_mask:0xf bank_mask:0xf bound_ctrl:1
	s_nop 0
	v_add_f32_dpp v47, v47, v47 row_shr:2 row_mask:0xf bank_mask:0xf bound_ctrl:1
	v_add_f32_dpp v46, v46, v46 row_shr:8 row_mask:0xf bank_mask:0xf bound_ctrl:1
	v_add_f32_dpp v45, v45, v45 row_bcast:15 row_mask:0xa bank_mask:0xf
	v_add_f32_dpp v47, v47, v47 row_shr:4 row_mask:0xf bank_mask:0xf bound_ctrl:1
	v_max_f32_e32 v40, 0xc2a00000, v40
	s_nop 0
	v_add_f32_dpp v47, v47, v47 row_shr:8 row_mask:0xf bank_mask:0xf bound_ctrl:1
	v_add_f32_dpp v46, v46, v46 row_bcast:15 row_mask:0xa bank_mask:0xf
	v_mul_f32_e32 v40, 0x3fb8aa3b, v40
	v_cndmask_b32_e64 v130, 0, v194, s[42:43]
	v_add_f32_dpp v47, v47, v47 row_bcast:15 row_mask:0xa bank_mask:0xf
	v_exp_f32_e32 v190, v40
	v_max_f32_e32 v40, 0xc2a00000, v41
	v_mul_f32_e32 v40, 0x3fb8aa3b, v40
	v_exp_f32_e32 v191, v40
	v_max_f32_e32 v40, 0xc2a00000, v42
	v_mul_f32_e32 v40, 0x3fb8aa3b, v40
	v_exp_f32_e32 v192, v40
	v_max_f32_e32 v40, 0xc2a00000, v43
	v_mul_f32_e32 v40, 0x3fb8aa3b, v40
	v_exp_f32_e32 v193, v40
	v_max_f32_e32 v40, 0xc2a00000, v44
	v_mul_f32_e32 v40, 0x3fb8aa3b, v40
	v_exp_f32_e32 v194, v40
	v_max_f32_e32 v40, 0xc2a00000, v45
	v_mul_f32_e32 v40, 0x3fb8aa3b, v40
	v_cndmask_b32_e64 v132, 0, v195, s[42:43]
	v_exp_f32_e32 v195, v40
	v_max_f32_e32 v40, 0xc2a00000, v46
	v_mul_f32_e32 v40, 0x3fb8aa3b, v40
	v_exp_f32_e32 v196, v40
	v_max_f32_e32 v40, 0xc2a00000, v47
	v_mul_f32_e32 v40, 0x3fb8aa3b, v40
	v_exp_f32_e32 v197, v40
	ds_bpermute_b32 v40, v244, v190
	ds_bpermute_b32 v41, v244, v191
	ds_bpermute_b32 v42, v244, v192
	ds_bpermute_b32 v43, v244, v193
	ds_bpermute_b32 v44, v244, v194
	ds_bpermute_b32 v45, v244, v195
	ds_bpermute_b32 v46, v244, v196
	ds_bpermute_b32 v47, v244, v197
	v_cndmask_b32_e64 v124, 0, v198, s[42:43]
	v_cndmask_b32_e64 v125, 0, v199, s[42:43]
	v_cndmask_b32_e64 v126, 0, v200, s[42:43]
	v_cndmask_b32_e64 v127, 0, v201, s[42:43]
	v_cndmask_b32_e64 v131, 0, v203, s[42:43]
	v_cndmask_b32_e64 v133, 0, v204, s[42:43]
	v_rcp_f32_e32 v198, v190
	v_rcp_f32_e32 v199, v191
	v_rcp_f32_e32 v200, v192
	v_rcp_f32_e32 v201, v193
	v_rcp_f32_e32 v202, v194
	v_rcp_f32_e32 v203, v195
	v_rcp_f32_e32 v204, v196
	v_rcp_f32_e32 v205, v197
	v_cndmask_b32_e64 v75, 0, v75, s[42:43]
	v_cndmask_b32_e64 v77, 0, v77, s[42:43]
	v_mul_f32_e32 v124, v124, v190
	v_mul_f32_e32 v75, v75, v198
	v_mul_f32_e32 v125, v125, v191
	v_mul_f32_e32 v77, v77, v199
	v_mul_f32_e32 v126, v126, v192
	v_mul_f32_e32 v79, v79, v200
	v_mul_f32_e32 v127, v127, v193
	v_mul_f32_e32 v193, v128, v201
	v_mul_f32_e32 v128, v129, v194
	v_mul_f32_e32 v130, v130, v202
	v_mul_f32_e32 v129, v131, v195
	v_mul_f32_e32 v131, v132, v203
	v_mul_f32_e32 v187, v187, v204
	v_mul_f32_e32 v189, v189, v205
	s_waitcnt lgkmcnt(0)
	v_mul_f32_e32 v194, v130, v44
	v_mul_f32_e32 v132, v131, v45
	v_cvt_pk_bf16_f32 v124, v124, v125
	v_cvt_pk_bf16_f32 v125, v126, v127
	v_cvt_pk_bf16_f32 v126, v128, v129
	v_cvt_pk_bf16_f32 v128, v75, v77
	v_cvt_pk_bf16_f32 v129, v79, v193
	v_cvt_pk_bf16_f32 v130, v130, v131
	v_cvt_pk_bf16_f32 v131, v187, v189
	v_mul_f32_e32 v133, v133, v196
	v_mul_f32_e32 v188, v188, v197
	v_cvt_pk_bf16_f32 v127, v133, v188
	s_nop 1
	v_mfma_f32_32x32x16_bf16 v[2:17], v[128:131], v[124:127], v[2:17]
	v_mul_f32_e32 v190, v40, v75
	v_xor_b32_e32 v75, v71, v168
	v_mul_f32_e32 v191, v77, v41
	v_lshl_add_u32 v75, v75, 4, v167
	v_mul_f32_e32 v192, v79, v42
	v_mul_f32_e32 v198, v193, v43
	ds_write_b128 v75, v[124:127] offset:20480
	v_cvt_pk_bf16_f32 v75, v190, v191
	ds_write_b16 v73, v75
	ds_write_b16_d16_hi v73, v75 offset:64
	v_cvt_pk_bf16_f32 v75, v192, v198
	v_mul_f32_e32 v195, v187, v46
	v_mul_f32_e32 v196, v189, v47
	ds_write_b16 v73, v75 offset:128
	ds_write_b16_d16_hi v73, v75 offset:192
	v_cvt_pk_bf16_f32 v75, v194, v132
	ds_write_b16 v73, v75 offset:256
	ds_write_b16_d16_hi v73, v75 offset:320
	v_cvt_pk_bf16_f32 v75, v195, v196
	ds_write_b16 v73, v75 offset:384
	ds_write_b16_d16_hi v73, v75 offset:448
	s_and_saveexec_b64 s[0:1], s[4:5]
	s_cbranch_execz .LBB0_562
	v_add_u32_e32 v75, s57, v183
	ds_write_b128 v75, v[40:43]
	ds_write_b128 v75, v[44:47] offset:16
	s_branch .LBB0_562
.Lg32_562:
	s_or_b64 exec, exec, s[0:1]
	s_add_i32 s57, s57, 64
	s_add_i32 s63, s63, 16
	v_add_u32_e32 v73, 0x400, v73
	s_cmpk_eq_i32 s57, 0x100
	v_add_u32_e32 v71, 2, v71
	s_cbranch_scc1 .Lp2g_exit

.Lg32_p2g_mid:
	s_xor_b32 s99, s99, 1
	ds_read_b128 v[124:127], v75 offset:16384
	ds_read_b128 v[128:131], v75 offset:16400
	ds_read_b128 v[188:191], v75
	ds_read_b128 v[192:195], v75 offset:16
	ds_read_b128 v[196:199], v75 offset:1024
	ds_read_b128 v[200:203], v75 offset:1040
	ds_read_b128 v[204:207], v75 offset:2048
	ds_read_b128 v[210:213], v75 offset:2064
	ds_read_b128 v[214:217], v75 offset:3072
	ds_read_b128 v[218:221], v75 offset:3088
	s_waitcnt lgkmcnt(7)
	v_pk_fma_f32 v[126:127], v[52:53], v[190:191], v[126:127]
	v_pk_fma_f32 v[124:125], v[50:51], v[188:189], v[124:125]
	s_waitcnt lgkmcnt(6)
	v_pk_fma_f32 v[130:131], v[52:53], v[194:195], v[130:131]
	v_pk_fma_f32 v[128:129], v[50:51], v[192:193], v[128:129]
	s_waitcnt lgkmcnt(5)
	v_pk_fma_f32 v[126:127], v[28:29], v[198:199], v[126:127]
	v_pk_fma_f32 v[124:125], v[54:55], v[196:197], v[124:125]
	s_waitcnt lgkmcnt(4)
	v_pk_fma_f32 v[130:131], v[28:29], v[202:203], v[130:131]
	v_pk_fma_f32 v[128:129], v[54:55], v[200:201], v[128:129]
	s_waitcnt lgkmcnt(3)
	v_pk_fma_f32 v[126:127], v[82:83], v[206:207], v[126:127]
	v_pk_fma_f32 v[124:125], v[80:81], v[204:205], v[124:125]
	s_waitcnt lgkmcnt(2)
	v_pk_fma_f32 v[130:131], v[82:83], v[212:213], v[130:131]
	v_pk_fma_f32 v[128:129], v[80:81], v[210:211], v[128:129]
	s_waitcnt lgkmcnt(1)
	v_pk_fma_f32 v[132:133], v[30:31], v[216:217], v[126:127]
	v_pk_fma_f32 v[214:215], v[84:85], v[214:215], v[124:125]
	s_waitcnt lgkmcnt(0)
	v_pk_fma_f32 v[216:217], v[30:31], v[220:221], v[130:131]
	v_pk_fma_f32 v[218:219], v[84:85], v[218:219], v[128:129]
	ds_read_b128 v[124:127], v75 offset:4096
	ds_read_b128 v[128:131], v75 offset:4112
	ds_read_b128 v[188:191], v75 offset:5120
	ds_read_b128 v[192:195], v75 offset:5136
	ds_read_b128 v[196:199], v75 offset:6144
	ds_read_b128 v[200:203], v75 offset:6160
	ds_read_b128 v[204:207], v75 offset:7168
	ds_read_b128 v[210:213], v75 offset:7184
	s_waitcnt lgkmcnt(7)
	v_pk_fma_f32 v[126:127], v[88:89], v[126:127], v[132:133]
	v_pk_fma_f32 v[124:125], v[86:87], v[124:125], v[214:215]
	s_waitcnt lgkmcnt(6)
	v_pk_fma_f32 v[130:131], v[88:89], v[130:131], v[216:217]
	v_pk_fma_f32 v[128:129], v[86:87], v[128:129], v[218:219]
	s_waitcnt lgkmcnt(5)
	v_pk_fma_f32 v[126:127], v[24:25], v[190:191], v[126:127]
	v_pk_fma_f32 v[124:125], v[90:91], v[188:189], v[124:125]
	s_waitcnt lgkmcnt(4)
	v_pk_fma_f32 v[130:131], v[24:25], v[194:195], v[130:131]
	v_pk_fma_f32 v[128:129], v[90:91], v[192:193], v[128:129]
	s_waitcnt lgkmcnt(3)
	v_pk_fma_f32 v[126:127], v[94:95], v[198:199], v[126:127]
	v_pk_fma_f32 v[124:125], v[92:93], v[196:197], v[124:125]
	s_waitcnt lgkmcnt(2)
	v_pk_fma_f32 v[130:131], v[94:95], v[202:203], v[130:131]
	v_pk_fma_f32 v[128:129], v[92:93], v[200:201], v[128:129]
	s_waitcnt lgkmcnt(1)
	v_pk_fma_f32 v[132:133], v[26:27], v[206:207], v[126:127]
	v_pk_fma_f32 v[214:215], v[96:97], v[204:205], v[124:125]
	s_waitcnt lgkmcnt(0)
	v_pk_fma_f32 v[216:217], v[26:27], v[212:213], v[130:131]
	v_pk_fma_f32 v[218:219], v[96:97], v[210:211], v[128:129]
	ds_read_b128 v[124:127], v75 offset:8192
	ds_read_b128 v[128:131], v75 offset:8208
	ds_read_b128 v[188:191], v75 offset:9216
	ds_read_b128 v[192:195], v75 offset:9232
	ds_read_b128 v[196:199], v75 offset:10240
	ds_read_b128 v[200:203], v75 offset:10256
	ds_read_b128 v[204:207], v75 offset:11264
	ds_read_b128 v[210:213], v75 offset:11280
	s_waitcnt lgkmcnt(7)
	v_pk_fma_f32 v[126:127], v[100:101], v[126:127], v[132:133]
	v_pk_fma_f32 v[124:125], v[98:99], v[124:125], v[214:215]
	s_waitcnt lgkmcnt(6)
	v_pk_fma_f32 v[130:131], v[100:101], v[130:131], v[216:217]
	v_pk_fma_f32 v[128:129], v[98:99], v[128:129], v[218:219]
	s_waitcnt lgkmcnt(5)
	v_pk_fma_f32 v[126:127], v[20:21], v[190:191], v[126:127]
	v_pk_fma_f32 v[124:125], v[102:103], v[188:189], v[124:125]
	s_waitcnt lgkmcnt(4)
	v_pk_fma_f32 v[130:131], v[20:21], v[194:195], v[130:131]
	v_pk_fma_f32 v[128:129], v[102:103], v[192:193], v[128:129]
	s_waitcnt lgkmcnt(3)
	v_pk_fma_f32 v[126:127], v[106:107], v[198:199], v[126:127]
	v_pk_fma_f32 v[124:125], v[104:105], v[196:197], v[124:125]
	s_waitcnt lgkmcnt(2)
	v_pk_fma_f32 v[130:131], v[106:107], v[202:203], v[130:131]
	v_pk_fma_f32 v[128:129], v[104:105], v[200:201], v[128:129]
	s_waitcnt lgkmcnt(1)
	v_pk_fma_f32 v[132:133], v[22:23], v[206:207], v[126:127]
	v_pk_fma_f32 v[214:215], v[108:109], v[204:205], v[124:125]
	s_waitcnt lgkmcnt(0)
	v_pk_fma_f32 v[216:217], v[22:23], v[212:213], v[130:131]
	v_pk_fma_f32 v[218:219], v[108:109], v[210:211], v[128:129]
	ds_read_b128 v[124:127], v75 offset:12288
	ds_read_b128 v[128:131], v75 offset:12304
	ds_read_b128 v[188:191], v75 offset:13312
	ds_read_b128 v[192:195], v75 offset:13328
	ds_read_b128 v[196:199], v75 offset:14336
	ds_read_b128 v[200:203], v75 offset:14352
	ds_read_b128 v[204:207], v75 offset:15360
	ds_read_b128 v[210:213], v75 offset:15376
	s_waitcnt lgkmcnt(7)
	v_pk_fma_f32 v[124:125], v[110:111], v[124:125], v[214:215]
	s_waitcnt lgkmcnt(6)
	v_pk_fma_f32 v[130:131], v[112:113], v[130:131], v[216:217]
	s_waitcnt lgkmcnt(5)
	v_pk_fma_f32 v[124:125], v[114:115], v[188:189], v[124:125]
	v_pk_fma_f32 v[126:127], v[112:113], v[126:127], v[132:133]
	s_waitcnt lgkmcnt(4)
	v_pk_fma_f32 v[130:131], v[116:117], v[194:195], v[130:131]
	s_waitcnt lgkmcnt(3)
	v_pk_fma_f32 v[124:125], v[118:119], v[196:197], v[124:125]
	v_pk_fma_f32 v[128:129], v[110:111], v[128:129], v[218:219]
	v_pk_fma_f32 v[126:127], v[116:117], v[190:191], v[126:127]
	s_waitcnt lgkmcnt(2)
	v_pk_fma_f32 v[132:133], v[120:121], v[202:203], v[130:131]
	s_waitcnt lgkmcnt(1)
	v_pk_fma_f32 v[130:131], v[122:123], v[204:205], v[124:125]
	v_pk_fma_f32 v[128:129], v[114:115], v[192:193], v[128:129]
	v_pk_fma_f32 v[126:127], v[120:121], v[198:199], v[126:127]
	v_mul_f32_e64 v75, |v130|, s80
	v_pk_fma_f32 v[188:189], v[118:119], v[200:201], v[128:129]
	v_pk_fma_f32 v[128:129], v[18:19], v[206:207], v[126:127]
	v_exp_f32_e32 v75, v75
	s_waitcnt lgkmcnt(0)
	v_pk_fma_f32 v[124:125], v[18:19], v[212:213], v[132:133]
	v_pk_fma_f32 v[126:127], v[122:123], v[210:211], v[188:189]
	v_mul_f32_e64 v132, |v129|, s80
	v_exp_f32_e32 v187, v132
	v_mul_f32_e64 v132, |v126|, s80
	v_exp_f32_e32 v190, v132
	v_mul_f32_e64 v132, |v127|, s80
	v_exp_f32_e32 v191, v132
	v_mul_f32_e64 v132, |v124|, s80
	v_add_f32_e32 v75, 1.0, v75
	v_exp_f32_e32 v192, v132
	v_mul_f32_e64 v132, |v125|, s80
	v_exp_f32_e32 v193, v132
	v_mul_f32_e64 v77, |v131|, s80
	v_log_f32_e32 v75, v75
	v_exp_f32_e32 v77, v77
	v_mul_f32_e64 v79, |v128|, s80
	v_exp_f32_e32 v79, v79
	v_mul_f32_e32 v132, 0x3f317217, v75
	v_fma_f32 v132, v75, s10, -v132
	v_fmac_f32_e32 v132, 0x3377d1cf, v75
	v_fmac_f32_e32 v132, 0x3f317217, v75
	v_min_f32_e32 v130, 0, v130
	v_min_f32_e32 v131, 0, v131
	v_mov_b32_e32 v132, v132
	v_add_f32_e32 v75, 1.0, v77
	v_min_f32_e32 v128, 0, v128
	v_min_f32_e32 v129, 0, v129
	v_log_f32_e32 v75, v75
	v_lshlrev_b32_e32 v194, 16, v46
	v_and_b32_e32 v195, 0xffff0000, v46
	v_lshlrev_b32_e32 v196, 16, v47
	v_mul_f32_e32 v77, 0x3f317217, v75
	v_fma_f32 v77, v75, s10, -v77
	v_fmac_f32_e32 v77, 0x3377d1cf, v75
	v_fmac_f32_e32 v77, 0x3f317217, v75
	v_and_b32_e32 v197, 0xffff0000, v47
	v_lshlrev_b32_e32 v46, 16, v42
	v_mov_b32_e32 v133, v77
	v_add_f32_e32 v75, 1.0, v79
	v_lshlrev_b32_e32 v79, 16, v45
	v_and_b32_e32 v42, 0xffff0000, v42
	v_log_f32_e32 v75, v75
	v_lshlrev_b32_e32 v47, 16, v43
	v_and_b32_e32 v43, 0xffff0000, v43
	v_mul_f32_e32 v203, 0x3e000000, v42
	v_mul_f32_e32 v77, 0x3f317217, v75
	v_fma_f32 v77, v75, s10, -v77
	v_fmac_f32_e32 v77, 0x3377d1cf, v75
	v_fmac_f32_e32 v77, 0x3f317217, v75
	v_mul_f32_e32 v205, 0x3e000000, v43
	v_min_f32_e32 v126, 0, v126
	v_mov_b32_e32 v188, v77
	v_add_f32_e32 v75, 1.0, v187
	v_and_b32_e32 v187, 0xffff0000, v45
	v_lshlrev_b32_e32 v45, 16, v41
	v_log_f32_e32 v75, v75
	v_and_b32_e32 v41, 0xffff0000, v41
	v_mul_f32_e32 v201, 0x3e000000, v41
	v_min_f32_e32 v127, 0, v127
	v_mul_f32_e32 v77, 0x3f317217, v75
	v_fma_f32 v77, v75, s10, -v77
	v_fmac_f32_e32 v77, 0x3377d1cf, v75
	v_fmac_f32_e32 v77, 0x3f317217, v75
	v_mul_f32_e32 v200, 0x3e000000, v45
	v_min_f32_e32 v124, 0, v124
	v_mov_b32_e32 v189, v77
	v_add_f32_e32 v75, 1.0, v190
	v_pk_add_f32 v[42:43], v[128:129], v[188:189] neg_lo:[0,1] neg_hi:[0,1]
	v_min_f32_e32 v125, 0, v125
	v_log_f32_e32 v75, v75
	v_pk_mul_f32 v[42:43], v[42:43], s[92:93] op_sel_hi:[1,0]
	v_mul_f32_e32 v202, 0x3e000000, v46
	v_mul_f32_e32 v77, 0x3f317217, v75
	v_fma_f32 v77, v75, s10, -v77
	v_fmac_f32_e32 v77, 0x3377d1cf, v75
	v_fmac_f32_e32 v77, 0x3f317217, v75
	v_add_f32_dpp v42, v42, v42 row_shr:1 row_mask:0xf bank_mask:0xf bound_ctrl:1
	v_mov_b32_e32 v190, v77
	v_add_f32_e32 v75, 1.0, v191
	v_add_f32_dpp v42, v42, v42 row_shr:2 row_mask:0xf bank_mask:0xf bound_ctrl:1
	v_add_f32_dpp v43, v43, v43 row_shr:1 row_mask:0xf bank_mask:0xf bound_ctrl:1
	v_log_f32_e32 v75, v75
	v_add_f32_dpp v42, v42, v42 row_shr:4 row_mask:0xf bank_mask:0xf bound_ctrl:1
	v_add_f32_dpp v43, v43, v43 row_shr:2 row_mask:0xf bank_mask:0xf bound_ctrl:1
	v_mul_f32_e32 v204, 0x3e000000, v47
	v_mul_f32_e32 v77, 0x3f317217, v75
	v_fma_f32 v77, v75, s10, -v77
	v_fmac_f32_e32 v77, 0x3377d1cf, v75
	v_fmac_f32_e32 v77, 0x3f317217, v75
	v_add_f32_dpp v42, v42, v42 row_shr:8 row_mask:0xf bank_mask:0xf bound_ctrl:1
	v_add_f32_dpp v43, v43, v43 row_shr:4 row_mask:0xf bank_mask:0xf bound_ctrl:1
	v_mov_b32_e32 v191, v77
	v_add_f32_e32 v75, 1.0, v192
	v_add_f32_dpp v43, v43, v43 row_shr:8 row_mask:0xf bank_mask:0xf bound_ctrl:1
	v_cndmask_b32_e64 v128, 0, v187, s[42:43]
	v_log_f32_e32 v75, v75
	v_cndmask_b32_e64 v187, 0, v196, s[42:43]
	v_cndmask_b32_e64 v189, 0, v197, s[42:43]
	v_cndmask_b32_e64 v129, 0, v202, s[42:43]
	v_mul_f32_e32 v77, 0x3f317217, v75
	v_fma_f32 v77, v75, s10, -v77
	v_fmac_f32_e32 v77, 0x3377d1cf, v75
	v_fmac_f32_e32 v77, 0x3f317217, v75
	v_cndmask_b32_e64 v188, 0, v205, s[42:43]
	v_mov_b32_e32 v192, v77
	v_add_f32_e32 v75, 1.0, v193
	s_nop 1
	v_log_f32_e32 v75, v75
	s_nop 0
	v_mul_f32_e32 v77, 0x3f317217, v75
	v_fma_f32 v77, v75, s10, -v77
	v_fmac_f32_e32 v77, 0x3377d1cf, v75
	v_fmac_f32_e32 v77, 0x3f317217, v75
	s_nop 1
	v_mov_b32_e32 v193, v77
	v_lshlrev_b32_e32 v75, 16, v44
	v_and_b32_e32 v77, 0xffff0000, v44
	v_lshlrev_b32_e32 v44, 16, v40
	v_and_b32_e32 v40, 0xffff0000, v40
	v_mul_f32_e32 v199, 0x3e000000, v40
	v_pk_add_f32 v[40:41], v[130:131], v[132:133] neg_lo:[0,1] neg_hi:[0,1]
	v_mul_f32_e32 v198, 0x3e000000, v44
	v_pk_mul_f32 v[40:41], v[40:41], s[92:93] op_sel_hi:[1,0]
	v_pk_add_f32 v[44:45], v[126:127], v[190:191] neg_lo:[0,1] neg_hi:[0,1]
	s_nop 0
	v_add_f32_dpp v40, v40, v40 row_shr:1 row_mask:0xf bank_mask:0xf bound_ctrl:1
	v_add_f32_dpp v41, v41, v41 row_shr:1 row_mask:0xf bank_mask:0xf bound_ctrl:1
	v_pk_mul_f32 v[44:45], v[44:45], s[92:93] op_sel_hi:[1,0]
	v_add_f32_dpp v40, v40, v40 row_shr:2 row_mask:0xf bank_mask:0xf bound_ctrl:1
	v_add_f32_dpp v41, v41, v41 row_shr:2 row_mask:0xf bank_mask:0xf bound_ctrl:1
	s_nop 0
	v_add_f32_dpp v40, v40, v40 row_shr:4 row_mask:0xf bank_mask:0xf bound_ctrl:1
	v_add_f32_dpp v41, v41, v41 row_shr:4 row_mask:0xf bank_mask:0xf bound_ctrl:1
	v_add_f32_dpp v44, v44, v44 row_shr:1 row_mask:0xf bank_mask:0xf bound_ctrl:1
	v_add_f32_dpp v40, v40, v40 row_shr:8 row_mask:0xf bank_mask:0xf bound_ctrl:1
	v_add_f32_dpp v41, v41, v41 row_shr:8 row_mask:0xf bank_mask:0xf bound_ctrl:1
	v_pk_add_f32 v[46:47], v[124:125], v[192:193] neg_lo:[0,1] neg_hi:[0,1]
	v_add_f32_dpp v40, v40, v40 row_bcast:15 row_mask:0xa bank_mask:0xf
	v_add_f32_dpp v44, v44, v44 row_shr:2 row_mask:0xf bank_mask:0xf bound_ctrl:1
	v_add_f32_dpp v41, v41, v41 row_bcast:15 row_mask:0xa bank_mask:0xf
	v_pk_mul_f32 v[46:47], v[46:47], s[92:93] op_sel_hi:[1,0]
	v_add_f32_dpp v45, v45, v45 row_shr:1 row_mask:0xf bank_mask:0xf bound_ctrl:1
	v_add_f32_dpp v42, v42, v42 row_bcast:15 row_mask:0xa bank_mask:0xf
	v_add_f32_dpp v44, v44, v44 row_shr:4 row_mask:0xf bank_mask:0xf bound_ctrl:1
	v_add_f32_dpp v45, v45, v45 row_shr:2 row_mask:0xf bank_mask:0xf bound_ctrl:1
	s_nop 0
	v_add_f32_dpp v44, v44, v44 row_shr:8 row_mask:0xf bank_mask:0xf bound_ctrl:1
	v_add_f32_dpp v43, v43, v43 row_bcast:15 row_mask:0xa bank_mask:0xf
	v_add_f32_dpp v46, v46, v46 row_shr:1 row_mask:0xf bank_mask:0xf bound_ctrl:1
	v_add_f32_dpp v45, v45, v45 row_shr:4 row_mask:0xf bank_mask:0xf bound_ctrl:1
	s_nop 0
	v_add_f32_dpp v46, v46, v46 row_shr:2 row_mask:0xf bank_mask:0xf bound_ctrl:1
	v_add_f32_dpp v45, v45, v45 row_shr:8 row_mask:0xf bank_mask:0xf bound_ctrl:1
	v_add_f32_dpp v44, v44, v44 row_bcast:15 row_mask:0xa bank_mask:0xf
	v_add_f32_dpp v47, v47, v47 row_shr:1 row_mask:0xf bank_mask:0xf bound_ctrl:1
	v_add_f32_dpp v46, v46, v46 row_shr:4 row_mask:0xf bank_mask:0xf bound_ctrl:1
	s_nop 0
	v_add_f32_dpp v47, v47, v47 row_shr:2 row_mask:0xf bank_mask:0xf bound_ctrl:1
	v_add_f32_dpp v46, v46, v46 row_shr:8 row_mask:0xf bank_mask:0xf bound_ctrl:1
	v_add_f32_dpp v45, v45, v45 row_bcast:15 row_mask:0xa bank_mask:0xf
	v_add_f32_dpp v47, v47, v47 row_shr:4 row_mask:0xf bank_mask:0xf bound_ctrl:1
	v_max_f32_e32 v40, 0xc2a00000, v40
	s_nop 0
	v_add_f32_dpp v47, v47, v47 row_shr:8 row_mask:0xf bank_mask:0xf bound_ctrl:1
	v_add_f32_dpp v46, v46, v46 row_bcast:15 row_mask:0xa bank_mask:0xf
	v_mul_f32_e32 v40, 0x3fb8aa3b, v40
	v_cndmask_b32_e64 v130, 0, v194, s[42:43]
	v_add_f32_dpp v47, v47, v47 row_bcast:15 row_mask:0xa bank_mask:0xf
	v_exp_f32_e32 v190, v40
	v_max_f32_e32 v40, 0xc2a00000, v41
	v_mul_f32_e32 v40, 0x3fb8aa3b, v40
	v_exp_f32_e32 v191, v40
	v_max_f32_e32 v40, 0xc2a00000, v42
	v_mul_f32_e32 v40, 0x3fb8aa3b, v40
	v_exp_f32_e32 v192, v40
	v_max_f32_e32 v40, 0xc2a00000, v43
	v_mul_f32_e32 v40, 0x3fb8aa3b, v40
	v_exp_f32_e32 v193, v40
	v_max_f32_e32 v40, 0xc2a00000, v44
	v_mul_f32_e32 v40, 0x3fb8aa3b, v40
	v_exp_f32_e32 v194, v40
	v_max_f32_e32 v40, 0xc2a00000, v45
	v_mul_f32_e32 v40, 0x3fb8aa3b, v40
	v_cndmask_b32_e64 v132, 0, v195, s[42:43]
	v_exp_f32_e32 v195, v40
	v_max_f32_e32 v40, 0xc2a00000, v46
	v_mul_f32_e32 v40, 0x3fb8aa3b, v40
	v_exp_f32_e32 v196, v40
	v_max_f32_e32 v40, 0xc2a00000, v47
	v_mul_f32_e32 v40, 0x3fb8aa3b, v40
	v_exp_f32_e32 v197, v40
	ds_bpermute_b32 v40, v244, v190
	ds_bpermute_b32 v41, v244, v191
	ds_bpermute_b32 v42, v244, v192
	ds_bpermute_b32 v43, v244, v193
	ds_bpermute_b32 v44, v244, v194
	ds_bpermute_b32 v45, v244, v195
	ds_bpermute_b32 v46, v244, v196
	ds_bpermute_b32 v47, v244, v197
	v_cndmask_b32_e64 v124, 0, v198, s[42:43]
	v_cndmask_b32_e64 v125, 0, v199, s[42:43]
	v_cndmask_b32_e64 v126, 0, v200, s[42:43]
	v_cndmask_b32_e64 v127, 0, v201, s[42:43]
	v_cndmask_b32_e64 v131, 0, v203, s[42:43]
	v_cndmask_b32_e64 v133, 0, v204, s[42:43]
	v_rcp_f32_e32 v198, v190
	v_rcp_f32_e32 v199, v191
	v_rcp_f32_e32 v200, v192
	v_rcp_f32_e32 v201, v193
	v_rcp_f32_e32 v202, v194
	v_rcp_f32_e32 v203, v195
	v_rcp_f32_e32 v204, v196
	v_rcp_f32_e32 v205, v197
	v_mul_f32_e32 v124, v124, v190
	v_mul_f32_e32 v75, v75, v198
	v_mul_f32_e32 v125, v125, v191
	v_mul_f32_e32 v77, v77, v199
	v_mul_f32_e32 v126, v126, v192
	v_mul_f32_e32 v79, v79, v200
	v_mul_f32_e32 v127, v127, v193
	v_mul_f32_e32 v193, v128, v201
	v_mul_f32_e32 v128, v129, v194
	v_mul_f32_e32 v130, v130, v202
	v_mul_f32_e32 v129, v131, v195
	v_mul_f32_e32 v131, v132, v203
	v_mul_f32_e32 v187, v187, v204
	v_mul_f32_e32 v189, v189, v205
	s_waitcnt lgkmcnt(0)
	v_mul_f32_e32 v194, v130, v44
	v_mul_f32_e32 v132, v131, v45
	v_cvt_pk_bf16_f32 v124, v124, v125
	v_cvt_pk_bf16_f32 v125, v126, v127
	v_cvt_pk_bf16_f32 v126, v128, v129
	v_cvt_pk_bf16_f32 v128, v75, v77
	v_cvt_pk_bf16_f32 v129, v79, v193
	v_cvt_pk_bf16_f32 v130, v130, v131
	v_cvt_pk_bf16_f32 v131, v187, v189
	v_mul_f32_e32 v133, v133, v196
	v_mul_f32_e32 v188, v188, v197
	v_cvt_pk_bf16_f32 v127, v133, v188
	s_nop 1
	v_mfma_f32_32x32x16_bf16 v[2:17], v[128:131], v[124:127], v[2:17]
	v_mul_f32_e32 v190, v40, v75
	v_xor_b32_e32 v75, v71, v168
	v_mul_f32_e32 v191, v77, v41
	v_lshl_add_u32 v75, v75, 4, v167
	v_mul_f32_e32 v192, v79, v42
	v_mul_f32_e32 v198, v193, v43
	ds_write_b128 v75, v[124:127] offset:20480
	v_cvt_pk_bf16_f32 v75, v190, v191
	ds_write_b16 v73, v75
	ds_write_b16_d16_hi v73, v75 offset:64
	v_cvt_pk_bf16_f32 v75, v192, v198
	v_mul_f32_e32 v195, v187, v46
	v_mul_f32_e32 v196, v189, v47
	ds_write_b16 v73, v75 offset:128
	ds_write_b16_d16_hi v73, v75 offset:192
	v_cvt_pk_bf16_f32 v75, v194, v132
	ds_write_b16 v73, v75 offset:256
	ds_write_b16_d16_hi v73, v75 offset:320
	v_cvt_pk_bf16_f32 v75, v195, v196
	ds_write_b16 v73, v75 offset:384
	ds_write_b16_d16_hi v73, v75 offset:448
	s_and_saveexec_b64 s[0:1], s[4:5]
	s_cbranch_execz .Lg32_562
	v_add_u32_e32 v75, s57, v183
	ds_write_b128 v75, v[40:43]
	ds_write_b128 v75, v[44:47] offset:16
	s_branch .Lg32_562
